# v27 + LRU pass 2: first chunk's 16 loads issued before wave 0's carry flag wait (overlap fetch with flag/carry round trips)
# speedup vs baseline: 1.0068x; 1.0029x over previous
.LBB0_759:
	v_mov_b32_e32 v25, v204
	s_and_b64 vcc, exec, s[38:39]
	v_and_b32_e32 v24, 63, v25
	s_movk_i32 s90, 0x4000
	s_movk_i32 s91, 0x2000
	s_mov_b32 s92, 0x8000
	s_mov_b32 s93, 0xa000
	s_mov_b32 s95, 0xe000
	s_movk_i32 s50, 0x3000
	s_movk_i32 s51, 0x7000
	s_mov_b32 s56, 0x9000
	s_mov_b32 s57, 0xb000
	s_mov_b32 s58, 0xd000
	s_mov_b32 s52, 0xf000
	s_movk_i32 s53, 0x110
	s_mov_b32 s59, 0x13000
	s_mov_b32 s60, 0x19000
	s_mov_b32 s61, 0x1f000
	s_mov_b32 s63, 0x25000
	s_mov_b64 s[88:89], 0x1000
	s_mov_b32 s75, s23
	v_readlane_b32 s34, v254, 37
	v_readlane_b32 s20, v254, 32
	v_readlane_b32 s0, v255, 0
	v_readlane_b32 s2, v255, 1
	s_add_i32 s28, s0, s2
	s_ashr_i32 s29, s28, 31
	s_lshl_b64 s[28:29], s[28:29], 12
	v_readlane_b32 s2, v254, 60
	v_readlane_b32 s3, v254, 61
	s_add_u32 s22, s2, s28
	s_addc_u32 s23, s3, s29
	v_lshlrev_b32_e32 v26, 2, v24
	s_nop 1
	global_load_dword v20, v26, s[22:23] nt
	global_load_dword v21, v26, s[22:23] offset:256 nt
	global_load_dword v22, v26, s[22:23] offset:512 nt
	global_load_dword v23, v26, s[22:23] offset:768 nt
	global_load_dword v34, v26, s[22:23] offset:1024 nt
	global_load_dword v35, v26, s[22:23] offset:1280 nt
	global_load_dword v36, v26, s[22:23] offset:1536 nt
	global_load_dword v37, v26, s[22:23] offset:1792 nt
	global_load_dword v39, v26, s[22:23] offset:2048 nt
	global_load_dword v40, v26, s[22:23] offset:2304 nt
	global_load_dword v41, v26, s[22:23] offset:2560 nt
	global_load_dword v45, v26, s[22:23] offset:2816 nt
	global_load_dword v51, v26, s[22:23] offset:3072 nt
	global_load_dword v58, v26, s[22:23] offset:3328 nt
	global_load_dword v59, v26, s[22:23] offset:3584 nt
	global_load_dword v60, v26, s[22:23] offset:3840 nt
	s_cbranch_vccnz .LBB0_771
	v_readlane_b32 s2, v254, 26
	v_readlane_b32 s0, v254, 39
	s_lshl_b32 s9, s2, 8
	s_and_b32 s40, s0, -8
	s_add_i32 s28, s40, s9
	s_ashr_i32 s29, s28, 31
	s_lshl_b64 s[28:29], s[28:29], 8
	s_add_u32 s28, s36, s28
	s_addc_u32 s29, s37, s29
	v_lshlrev_b32_e32 v2, 8, v24
	v_lshl_add_u64 v[4:5], s[28:29], 0, v[2:3]
	s_mov_b64 s[28:29], 0x180000
	v_cmp_gt_u32_e64 s[38:39], s20, v24
	v_lshl_add_u64 v[4:5], v[4:5], 0, s[28:29]
	v_mov_b32_e32 v2, 0x400000
	v_readlane_b32 s3, v254, 27
	s_branch .LBB0_762

.LBB0_771:
	v_readlane_b32 s0, v255, 0
	v_readlane_b32 s2, v255, 1
	s_add_i32 s28, s0, s2
	s_ashr_i32 s29, s28, 31
	s_lshl_b64 s[28:29], s[28:29], 12
	v_readlane_b32 s2, v254, 60
	v_readlane_b32 s3, v254, 61
	s_add_u32 s22, s2, s28
	s_addc_u32 s23, s3, s29
	v_readlane_b32 s2, v253, 9
	v_readlane_b32 s28, v254, 57
	v_lshlrev_b32_e32 v2, 2, v24
	v_readlane_b32 s3, v253, 10
	v_readlane_b32 s29, v254, 58
	v_ashrrev_i32_e32 v30, 3, v25
	v_lshl_add_u64 v[26:27], s[22:23], 0, v[2:3]
	s_or_b64 s[22:23], s[28:29], s[2:3]
	v_ashrrev_i32_e32 v31, 31, v30
	v_lshl_add_u64 v[4:5], s[22:23], 0, v[30:31]
	v_mov_b64_e32 v[6:7], s[54:55]
	v_mad_u64_u32 v[8:9], s[22:23], v4, s16, v[6:7]
	s_and_b32 s1, s1, 0x3c0
	v_mad_i32_i24 v9, v5, s16, v9
	s_lshl_b32 s24, s1, 1
	v_and_b32_e32 v70, 7, v25
	v_lshl_add_u64 v[4:5], v[8:9], 0, s[24:25]
	v_lshlrev_b32_e32 v2, 4, v70
	v_lshl_add_u64 v[4:5], v[4:5], 0, v[2:3]
	s_mov_b32 s0, 0x60000
	v_add_co_u32_e32 v8, vcc, s0, v4
	v_lshl_add_u64 v[28:29], s[28:29], 0, v[30:31]
	s_nop 0
	v_addc_co_u32_e32 v9, vcc, 0, v5, vcc
	global_load_dwordx4 v[16:19], v[4:5], off offset:2048
	s_nop 0
	global_load_dwordx4 v[8:11], v[8:9], off offset:2048
	v_add_co_u32_e32 v4, vcc, s92, v26
	s_bitset1_b32 s2, 7
	s_nop 0
	v_addc_co_u32_e32 v5, vcc, 0, v27, vcc
	global_load_dword v86, v[4:5], off nt
	global_load_dword v85, v[4:5], off offset:256 nt
	global_load_dword v84, v[4:5], off offset:512 nt
	global_load_dword v83, v[4:5], off offset:768 nt
	global_load_dword v82, v[4:5], off offset:1024 nt
	global_load_dword v81, v[4:5], off offset:1280 nt
	global_load_dword v80, v[4:5], off offset:1536 nt
	global_load_dword v79, v[4:5], off offset:1792 nt
	global_load_dword v78, v[4:5], off offset:2048 nt
	global_load_dword v77, v[4:5], off offset:2304 nt
	global_load_dword v76, v[4:5], off offset:2560 nt
	global_load_dword v75, v[4:5], off offset:2816 nt
	global_load_dword v74, v[4:5], off offset:3072 nt
	global_load_dword v73, v[4:5], off offset:3328 nt
	global_load_dword v67, v[4:5], off offset:3584 nt
	global_load_dword v66, v[4:5], off offset:3840 nt
	s_mov_b32 s3, s25
	v_lshl_add_u64 v[32:33], v[28:29], 0, s[2:3]
	v_mad_u64_u32 v[4:5], s[2:3], v32, s16, v[6:7]
	v_mad_i32_i24 v5, v33, s16, v5
	v_lshl_add_u64 v[4:5], v[4:5], 0, s[24:25]
	v_lshl_add_u64 v[4:5], v[4:5], 0, v[2:3]
	v_add_co_u32_e32 v6, vcc, s0, v4
	v_and_b32_e32 v68, 31, v25
	s_nop 0
	v_addc_co_u32_e32 v7, vcc, 0, v5, vcc
	global_load_dwordx4 v[12:15], v[4:5], off offset:2048
	s_nop 0
	global_load_dwordx4 v[4:7], v[6:7], off offset:2048
	v_readlane_b32 s0, v254, 29
	s_mov_b32 s14, 0x60000
	v_cmp_gt_u32_e64 s[38:39], 32, v24
	v_lshl_add_u32 v71, v68, 3, s0
	s_waitcnt vmcnt(35)
	v_lshlrev_b32_e32 v31, 16, v20
	v_exp_f32_e32 v50, v31
	v_and_b32_e32 v54, 0xffff0000, v20
	s_waitcnt vmcnt(34)
	v_lshlrev_b32_e32 v20, 16, v21
	v_and_b32_e32 v55, 0xffff0000, v21
	s_waitcnt vmcnt(33)
	v_lshlrev_b32_e32 v21, 16, v22
	v_and_b32_e32 v56, 0xffff0000, v22
	s_waitcnt vmcnt(32)
	v_lshlrev_b32_e32 v22, 16, v23
	v_and_b32_e32 v57, 0xffff0000, v23
	s_waitcnt vmcnt(31)
	v_lshlrev_b32_e32 v23, 16, v34
	v_and_b32_e32 v48, 0xffff0000, v34
	s_waitcnt vmcnt(28)
	v_lshlrev_b32_e32 v34, 16, v37
	v_exp_f32_e32 v20, v20
	v_exp_f32_e32 v44, v23
	v_lshlrev_b32_e32 v23, 16, v35
	v_and_b32_e32 v49, 0xffff0000, v35
	v_exp_f32_e32 v35, v34
	s_waitcnt vmcnt(27)
	v_lshlrev_b32_e32 v34, 16, v39
	v_exp_f32_e32 v21, v21
	v_exp_f32_e32 v38, v34
	s_waitcnt vmcnt(26)
	v_lshlrev_b32_e32 v34, 16, v40
	v_exp_f32_e32 v22, v22
	v_and_b32_e32 v42, 0xffff0000, v39
	v_exp_f32_e32 v39, v34
	s_waitcnt vmcnt(25)
	v_lshlrev_b32_e32 v34, 16, v41
	v_exp_f32_e32 v62, v34
	s_waitcnt vmcnt(24)
	v_lshlrev_b32_e32 v34, 16, v45
	v_fmac_f32_e32 v54, 0, v50
	v_exp_f32_e32 v23, v23
	v_lshlrev_b32_e32 v31, 16, v36
	v_exp_f32_e32 v63, v34
	s_waitcnt vmcnt(23)
	v_lshlrev_b32_e32 v34, 16, v51
	v_fmac_f32_e32 v55, v20, v54
	v_exp_f32_e32 v31, v31
	v_and_b32_e32 v53, 0xffff0000, v37
	v_exp_f32_e32 v34, v34
	s_waitcnt vmcnt(22)
	v_lshlrev_b32_e32 v37, 16, v58
	v_fmac_f32_e32 v56, v21, v55
	v_and_b32_e32 v43, 0xffff0000, v40
	v_exp_f32_e32 v69, v37
	s_waitcnt vmcnt(21)
	v_lshlrev_b32_e32 v40, 16, v59
	v_fmac_f32_e32 v57, v22, v56
	v_and_b32_e32 v52, 0xffff0000, v36
	v_and_b32_e32 v46, 0xffff0000, v41
	v_and_b32_e32 v36, 0xffff0000, v51
	v_exp_f32_e32 v72, v40
	s_waitcnt vmcnt(20)
	v_lshlrev_b32_e32 v41, 16, v60
	v_mul_f32_e32 v51, v50, v20
	v_fmac_f32_e32 v48, 0, v44
	ds_bpermute_b32 v20, v197, v57
	v_and_b32_e32 v47, 0xffff0000, v45
	v_exp_f32_e32 v87, v41
	v_mul_f32_e32 v64, v21, v51
	v_fmac_f32_e32 v49, v23, v48
	v_mul_f32_e32 v45, v44, v23
	v_and_b32_e32 v37, 0xffff0000, v58
	v_and_b32_e32 v41, 0xffff0000, v60
	v_mul_f32_e32 v65, v22, v64
	v_fmac_f32_e32 v52, v31, v49
	v_mul_f32_e32 v60, v31, v45
	v_fmac_f32_e32 v42, 0, v38
	v_fmac_f32_e32 v36, 0, v34
	v_and_b32_e32 v40, 0xffff0000, v59
	v_fmac_f32_e32 v53, v35, v52
	v_mul_f32_e32 v61, v35, v60
	v_fmac_f32_e32 v43, v39, v42
	v_mul_f32_e32 v39, v38, v39
	v_fmac_f32_e32 v37, v69, v36
	v_mul_f32_e32 v35, v34, v69
	ds_bpermute_b32 v31, v197, v65
	v_fmac_f32_e32 v46, v62, v43
	v_mul_f32_e32 v58, v62, v39
	v_fmac_f32_e32 v40, v72, v37
	v_mul_f32_e32 v62, v72, v35
	v_fmac_f32_e32 v47, v63, v46
	v_mul_f32_e32 v59, v63, v58
	v_fmac_f32_e32 v41, v87, v40
	v_mul_f32_e32 v63, v87, v62
	s_waitcnt lgkmcnt(1)
	v_cndmask_b32_e64 v87, v20, v57, s[38:39]
	v_cndmask_b32_e64 v88, v57, v20, s[38:39]
	ds_bpermute_b32 v20, v197, v61
	ds_bpermute_b32 v23, v197, v53
	s_waitcnt lgkmcnt(2)
	v_cndmask_b32_e64 v21, v31, v65, s[38:39]
	v_cndmask_b32_e64 v22, v65, v31, s[38:39]
	v_fmac_f32_e32 v87, 0, v21
	v_mul_f32_e32 v89, v65, v31
	v_fmac_f32_e32 v88, v22, v87
	s_waitcnt lgkmcnt(1)
	v_cndmask_b32_e64 v21, v20, v61, s[38:39]
	s_waitcnt lgkmcnt(0)
	v_cndmask_b32_e64 v90, v23, v53, s[38:39]
	v_cndmask_b32_e64 v91, v53, v23, s[38:39]
	ds_bpermute_b32 v22, v197, v59
	ds_bpermute_b32 v23, v197, v47
	v_cndmask_b32_e64 v20, v61, v20, s[38:39]
	v_mul_f32_e32 v92, v89, v21
	v_fmac_f32_e32 v90, v21, v88
	v_mul_f32_e32 v93, v20, v92
	v_fmac_f32_e32 v91, v20, v90
	ds_bpermute_b32 v21, v197, v63
	ds_bpermute_b32 v20, v197, v41
	s_waitcnt lgkmcnt(3)
	v_cndmask_b32_e64 v69, v22, v59, s[38:39]
	s_waitcnt lgkmcnt(2)
	v_cndmask_b32_e64 v94, v23, v47, s[38:39]
	v_cndmask_b32_e64 v22, v59, v22, s[38:39]
	v_cndmask_b32_e64 v95, v47, v23, s[38:39]
	v_mul_f32_e32 v96, v93, v69
	v_fmac_f32_e32 v94, v69, v91
	v_mul_f32_e32 v97, v22, v96
	v_fmac_f32_e32 v95, v22, v94
	s_waitcnt lgkmcnt(1)
	v_cndmask_b32_e64 v22, v21, v63, s[38:39]
	s_waitcnt lgkmcnt(0)
	v_cndmask_b32_e64 v98, v20, v41, s[38:39]
	v_mul_f32_e32 v99, v97, v22
	v_fmac_f32_e32 v98, v22, v95
	s_and_saveexec_b64 s[2:3], s[38:39]
	v_mul_f32_e32 v23, v98, v21
	v_mul_f32_e32 v22, v99, v21
	v_add_f32_e32 v23, v23, v20
	ds_write_b64 v71, v[22:23]
	s_or_b64 exec, exec, s[2:3]
	s_lshl_b32 s4, s34, 2
	s_add_i32 s2, s4, 0
	v_lshl_add_u32 v20, v68, 2, s2
	v_add_u32_e32 v69, 0x119c0, v20
	s_waitcnt lgkmcnt(0)
	s_barrier
	ds_read_b32 v23, v69
	s_cmp_gt_i32 s62, 0
	s_cselect_b64 s[22:23], -1, 0
	s_cmp_lt_i32 s62, 1
	s_cbranch_scc1 .LBB0_780
	s_add_i32 s2, s62, -1
	s_cmp_lt_u32 s2, 7
	s_mov_b32 s2, 0
	s_cbranch_scc1 .LBB0_777
	v_readlane_b32 s0, v254, 35
	s_add_i32 s3, s0, 0
	s_add_i32 s3, s3, 0x111c0
	s_and_b32 s2, s62, 0x7ffffff8
	v_lshl_add_u32 v72, v68, 3, s3
	s_mov_b32 s3, 0
